# ml_intra: key-tile staging remapped (thread owns one 8-channel column group for 8 rows); its block-transform weights stay in registers, 64 LDS weight reads per thread per item removed
# speedup vs baseline: 1.0169x; 1.0169x over previous
.LBB0_657:
	s_or_b64 exec, exec, s[2:3]
	s_mov_b64 s[2:3], s[66:67]
	s_waitcnt lgkmcnt(0)
	s_barrier
	s_load_dwordx2 s[10:11], s[2:3], 0x120
	s_nop 0
	s_load_dwordx2 s[2:3], s[2:3], 0xf0
	s_waitcnt vmcnt(31)
	v_mov_b32_e32 v42, v178
	s_mov_b32 s4, s68
	s_waitcnt lgkmcnt(0)
	s_add_u32 s46, s10, 0x13200000
	s_addc_u32 s47, s11, 0
	v_ashrrev_i32_e32 v44, 3, v42
	v_and_b32_e32 v36, 7, v42
	s_cmpk_gt_i32 s4, 0x7ff
	v_ashrrev_i32_e32 v45, 31, v44
	v_lshlrev_b32_e32 v34, 4, v36
	v_lshrrev_b32_e32 v236, 6, v178
	v_mov_b32_e32 v237, 0
	v_and_b32_e32 v238, 63, v178
	v_lshlrev_b32_e32 v247, 7, v238
	v_add_u32_e32 v247, 0x12400, v247
	v_lshlrev_b32_e32 v238, 4, v238
	v_mov_b32_e32 v239, 0
	v_mov_b32_e32 v252, 0x8000
	v_mov_b32_e32 v253, 0
	v_mul_u32_u24_e32 v246, 0x410, v236
	v_add_u32_e32 v246, v246, v238
	s_cbranch_scc1 .LBB0_659
	s_ashr_i32 s6, s4, 9
	s_ashr_i32 s7, s6, 31
	s_lshl_b32 s5, s4, 4
	s_and_b32 s80, s5, 0x1fc0
	s_lshl_b64 s[6:7], s[6:7], 25
	v_lshl_add_u64 v[2:3], s[80:81], 0, v[236:237]
	s_add_u32 s6, s46, s6
	v_lshlrev_b64 v[2:3], 12, v[2:3]
	s_addc_u32 s7, s47, s7
	s_lshl_b32 s4, s4, 10
	v_lshl_add_u64 v[2:3], s[6:7], 0, v[2:3]
	s_and_b32 s80, s4, 0xc00
	v_lshl_add_u64 v[2:3], v[2:3], 0, s[80:81]
	v_mov_b32_e32 v35, v0
	v_lshl_add_u64 v[232:233], v[2:3], 0, v[238:239]
	global_load_dwordx4 v[2:5], v[232:233], off
	v_lshl_add_u64 v[232:233], v[232:233], 0, v[252:253]
	global_load_dwordx4 v[6:9], v[232:233], off
	v_lshl_add_u64 v[232:233], v[232:233], 0, v[252:253]
	global_load_dwordx4 v[10:13], v[232:233], off
	v_lshl_add_u64 v[232:233], v[232:233], 0, v[252:253]
	global_load_dwordx4 v[14:17], v[232:233], off
	v_lshl_add_u64 v[232:233], v[232:233], 0, v[252:253]
	global_load_dwordx4 v[18:21], v[232:233], off
	v_lshl_add_u64 v[232:233], v[232:233], 0, v[252:253]
	global_load_dwordx4 v[22:25], v[232:233], off
	v_lshl_add_u64 v[232:233], v[232:233], 0, v[252:253]
	global_load_dwordx4 v[26:29], v[232:233], off
	v_lshl_add_u64 v[232:233], v[232:233], 0, v[252:253]
	global_load_dwordx4 v[30:33], v[232:233], off

.LBB0_673:
	s_or_b64 exec, exec, s[50:51]
	s_mov_b32 s62, s63
	s_waitcnt lgkmcnt(0)
	s_barrier
	ds_read_b128 v[204:207], v247
	ds_read_b128 v[208:211], v247 offset:16
	ds_read_b128 v[212:215], v247 offset:32
	ds_read_b128 v[216:219], v247 offset:48
	ds_read_b128 v[220:223], v247 offset:64
	ds_read_b128 v[224:227], v247 offset:80
	ds_read_b128 v[228:231], v247 offset:96
	ds_read_b128 v[248:251], v247 offset:112
	s_waitcnt lgkmcnt(0)
.LBB0_674:
	s_and_b32 s45, s33, 0xfffffe00
	s_lshl_b32 s50, s63, 7
	s_bfe_u32 s56, s33, 0x70002
	s_or_b32 s45, s50, s45
	s_or_b32 s52, s45, s56
	s_ashr_i32 s53, s52, 31
	s_ashr_i32 s44, s33, 9
	s_lshl_b64 s[50:51], s[52:53], 10
	s_add_u32 s50, s58, s50
	s_addc_u32 s51, s59, s51
	s_ashr_i32 s45, s44, 31
	s_lshl_b64 s[54:55], s[44:45], 13
	s_lshl_b32 s44, s56, 6
	s_or_b32 s54, s54, s44
	s_add_i32 s44, 0, 0x12400
	s_waitcnt vmcnt(15)
	s_waitcnt vmcnt(7)
	v_lshlrev_b32_e32 v108, 16, v2
	v_and_b32_e32 v110, 0xffff0000, v2
	v_lshlrev_b32_e32 v112, 16, v3
	v_and_b32_e32 v114, 0xffff0000, v3
	v_pk_mul_f32 v[100:101], v[208:209], v[110:111] op_sel_hi:[1,0]
	v_pk_mul_f32 v[102:103], v[210:211], v[110:111] op_sel_hi:[1,0]
	v_pk_fma_f32 v[100:101], v[204:205], v[108:109], v[100:101] op_sel_hi:[1,0,1]
	v_pk_fma_f32 v[102:103], v[206:207], v[108:109], v[102:103] op_sel_hi:[1,0,1]
	v_pk_fma_f32 v[100:101], v[212:213], v[112:113], v[100:101] op_sel_hi:[1,0,1]
	v_pk_fma_f32 v[102:103], v[214:215], v[112:113], v[102:103] op_sel_hi:[1,0,1]
	v_pk_fma_f32 v[34:35], v[216:217], v[114:115], v[100:101] op_sel_hi:[1,0,1]
	v_pk_fma_f32 v[36:37], v[218:219], v[114:115], v[102:103] op_sel_hi:[1,0,1]
	v_lshlrev_b32_e32 v116, 16, v4
	v_and_b32_e32 v118, 0xffff0000, v4
	v_lshlrev_b32_e32 v120, 16, v5
	v_and_b32_e32 v122, 0xffff0000, v5
	v_pk_mul_f32 v[100:101], v[224:225], v[118:119] op_sel_hi:[1,0]
	v_pk_mul_f32 v[102:103], v[226:227], v[118:119] op_sel_hi:[1,0]
	v_pk_fma_f32 v[100:101], v[220:221], v[116:117], v[100:101] op_sel_hi:[1,0,1]
	v_pk_fma_f32 v[102:103], v[222:223], v[116:117], v[102:103] op_sel_hi:[1,0,1]
	v_pk_fma_f32 v[100:101], v[228:229], v[120:121], v[100:101] op_sel_hi:[1,0,1]
	v_pk_fma_f32 v[102:103], v[230:231], v[120:121], v[102:103] op_sel_hi:[1,0,1]
	v_pk_fma_f32 v[38:39], v[248:249], v[122:123], v[100:101] op_sel_hi:[1,0,1]
	v_pk_fma_f32 v[40:41], v[250:251], v[122:123], v[102:103] op_sel_hi:[1,0,1]
	v_cvt_pk_bf16_f32 v104, v34, v35
	v_cvt_pk_bf16_f32 v105, v36, v37
	v_cvt_pk_bf16_f32 v106, v38, v39
	v_cvt_pk_bf16_f32 v107, v40, v41
	ds_write_b128 v246, v[104:107]
	s_waitcnt vmcnt(6)
	v_lshlrev_b32_e32 v108, 16, v6
	v_and_b32_e32 v110, 0xffff0000, v6
	v_lshlrev_b32_e32 v112, 16, v7
	v_and_b32_e32 v114, 0xffff0000, v7
	v_pk_mul_f32 v[100:101], v[208:209], v[110:111] op_sel_hi:[1,0]
	v_pk_mul_f32 v[102:103], v[210:211], v[110:111] op_sel_hi:[1,0]
	v_pk_fma_f32 v[100:101], v[204:205], v[108:109], v[100:101] op_sel_hi:[1,0,1]
	v_pk_fma_f32 v[102:103], v[206:207], v[108:109], v[102:103] op_sel_hi:[1,0,1]
	v_pk_fma_f32 v[100:101], v[212:213], v[112:113], v[100:101] op_sel_hi:[1,0,1]
	v_pk_fma_f32 v[102:103], v[214:215], v[112:113], v[102:103] op_sel_hi:[1,0,1]
	v_pk_fma_f32 v[34:35], v[216:217], v[114:115], v[100:101] op_sel_hi:[1,0,1]
	v_pk_fma_f32 v[36:37], v[218:219], v[114:115], v[102:103] op_sel_hi:[1,0,1]
	v_lshlrev_b32_e32 v116, 16, v8
	v_and_b32_e32 v118, 0xffff0000, v8
	v_lshlrev_b32_e32 v120, 16, v9
	v_and_b32_e32 v122, 0xffff0000, v9
	v_pk_mul_f32 v[100:101], v[224:225], v[118:119] op_sel_hi:[1,0]
	v_pk_mul_f32 v[102:103], v[226:227], v[118:119] op_sel_hi:[1,0]
	v_pk_fma_f32 v[100:101], v[220:221], v[116:117], v[100:101] op_sel_hi:[1,0,1]
	v_pk_fma_f32 v[102:103], v[222:223], v[116:117], v[102:103] op_sel_hi:[1,0,1]
	v_pk_fma_f32 v[100:101], v[228:229], v[120:121], v[100:101] op_sel_hi:[1,0,1]
	v_pk_fma_f32 v[102:103], v[230:231], v[120:121], v[102:103] op_sel_hi:[1,0,1]
	v_pk_fma_f32 v[38:39], v[248:249], v[122:123], v[100:101] op_sel_hi:[1,0,1]
	v_pk_fma_f32 v[40:41], v[250:251], v[122:123], v[102:103] op_sel_hi:[1,0,1]
	v_cvt_pk_bf16_f32 v104, v34, v35
	v_cvt_pk_bf16_f32 v105, v36, v37
	v_cvt_pk_bf16_f32 v106, v38, v39
	v_cvt_pk_bf16_f32 v107, v40, v41
	ds_write_b128 v246, v[104:107] offset:8320
	s_waitcnt vmcnt(5)
	v_lshlrev_b32_e32 v108, 16, v10
	v_and_b32_e32 v110, 0xffff0000, v10
	v_lshlrev_b32_e32 v112, 16, v11
	v_and_b32_e32 v114, 0xffff0000, v11
	v_pk_mul_f32 v[100:101], v[208:209], v[110:111] op_sel_hi:[1,0]
	v_pk_mul_f32 v[102:103], v[210:211], v[110:111] op_sel_hi:[1,0]
	v_pk_fma_f32 v[100:101], v[204:205], v[108:109], v[100:101] op_sel_hi:[1,0,1]
	v_pk_fma_f32 v[102:103], v[206:207], v[108:109], v[102:103] op_sel_hi:[1,0,1]
	v_pk_fma_f32 v[100:101], v[212:213], v[112:113], v[100:101] op_sel_hi:[1,0,1]
	v_pk_fma_f32 v[102:103], v[214:215], v[112:113], v[102:103] op_sel_hi:[1,0,1]
	v_pk_fma_f32 v[34:35], v[216:217], v[114:115], v[100:101] op_sel_hi:[1,0,1]
	v_pk_fma_f32 v[36:37], v[218:219], v[114:115], v[102:103] op_sel_hi:[1,0,1]
	v_lshlrev_b32_e32 v116, 16, v12
	v_and_b32_e32 v118, 0xffff0000, v12
	v_lshlrev_b32_e32 v120, 16, v13
	v_and_b32_e32 v122, 0xffff0000, v13
	v_pk_mul_f32 v[100:101], v[224:225], v[118:119] op_sel_hi:[1,0]
	v_pk_mul_f32 v[102:103], v[226:227], v[118:119] op_sel_hi:[1,0]
	v_pk_fma_f32 v[100:101], v[220:221], v[116:117], v[100:101] op_sel_hi:[1,0,1]
	v_pk_fma_f32 v[102:103], v[222:223], v[116:117], v[102:103] op_sel_hi:[1,0,1]
	v_pk_fma_f32 v[100:101], v[228:229], v[120:121], v[100:101] op_sel_hi:[1,0,1]
	v_pk_fma_f32 v[102:103], v[230:231], v[120:121], v[102:103] op_sel_hi:[1,0,1]
	v_pk_fma_f32 v[38:39], v[248:249], v[122:123], v[100:101] op_sel_hi:[1,0,1]
	v_pk_fma_f32 v[40:41], v[250:251], v[122:123], v[102:103] op_sel_hi:[1,0,1]
	v_cvt_pk_bf16_f32 v104, v34, v35
	v_cvt_pk_bf16_f32 v105, v36, v37
	v_cvt_pk_bf16_f32 v106, v38, v39
	v_cvt_pk_bf16_f32 v107, v40, v41
	ds_write_b128 v246, v[104:107] offset:16640
	s_waitcnt vmcnt(4)
	v_lshlrev_b32_e32 v108, 16, v14
	v_and_b32_e32 v110, 0xffff0000, v14
	v_lshlrev_b32_e32 v112, 16, v15
	v_and_b32_e32 v114, 0xffff0000, v15
	v_pk_mul_f32 v[100:101], v[208:209], v[110:111] op_sel_hi:[1,0]
	v_pk_mul_f32 v[102:103], v[210:211], v[110:111] op_sel_hi:[1,0]
	v_pk_fma_f32 v[100:101], v[204:205], v[108:109], v[100:101] op_sel_hi:[1,0,1]
	v_pk_fma_f32 v[102:103], v[206:207], v[108:109], v[102:103] op_sel_hi:[1,0,1]
	v_pk_fma_f32 v[100:101], v[212:213], v[112:113], v[100:101] op_sel_hi:[1,0,1]
	v_pk_fma_f32 v[102:103], v[214:215], v[112:113], v[102:103] op_sel_hi:[1,0,1]
	v_pk_fma_f32 v[34:35], v[216:217], v[114:115], v[100:101] op_sel_hi:[1,0,1]
	v_pk_fma_f32 v[36:37], v[218:219], v[114:115], v[102:103] op_sel_hi:[1,0,1]
	v_lshlrev_b32_e32 v116, 16, v16
	v_and_b32_e32 v118, 0xffff0000, v16
	v_lshlrev_b32_e32 v120, 16, v17
	v_and_b32_e32 v122, 0xffff0000, v17
	v_pk_mul_f32 v[100:101], v[224:225], v[118:119] op_sel_hi:[1,0]
	v_pk_mul_f32 v[102:103], v[226:227], v[118:119] op_sel_hi:[1,0]
	v_pk_fma_f32 v[100:101], v[220:221], v[116:117], v[100:101] op_sel_hi:[1,0,1]
	v_pk_fma_f32 v[102:103], v[222:223], v[116:117], v[102:103] op_sel_hi:[1,0,1]
	v_pk_fma_f32 v[100:101], v[228:229], v[120:121], v[100:101] op_sel_hi:[1,0,1]
	v_pk_fma_f32 v[102:103], v[230:231], v[120:121], v[102:103] op_sel_hi:[1,0,1]
	v_pk_fma_f32 v[38:39], v[248:249], v[122:123], v[100:101] op_sel_hi:[1,0,1]
	v_pk_fma_f32 v[40:41], v[250:251], v[122:123], v[102:103] op_sel_hi:[1,0,1]
	v_cvt_pk_bf16_f32 v104, v34, v35
	v_cvt_pk_bf16_f32 v105, v36, v37
	v_cvt_pk_bf16_f32 v106, v38, v39
	v_cvt_pk_bf16_f32 v107, v40, v41
	ds_write_b128 v246, v[104:107] offset:24960
	s_waitcnt vmcnt(3)
	v_lshlrev_b32_e32 v108, 16, v18
	v_and_b32_e32 v110, 0xffff0000, v18
	v_lshlrev_b32_e32 v112, 16, v19
	v_and_b32_e32 v114, 0xffff0000, v19
	v_pk_mul_f32 v[100:101], v[208:209], v[110:111] op_sel_hi:[1,0]
	v_pk_mul_f32 v[102:103], v[210:211], v[110:111] op_sel_hi:[1,0]
	v_pk_fma_f32 v[100:101], v[204:205], v[108:109], v[100:101] op_sel_hi:[1,0,1]
	v_pk_fma_f32 v[102:103], v[206:207], v[108:109], v[102:103] op_sel_hi:[1,0,1]
	v_pk_fma_f32 v[100:101], v[212:213], v[112:113], v[100:101] op_sel_hi:[1,0,1]
	v_pk_fma_f32 v[102:103], v[214:215], v[112:113], v[102:103] op_sel_hi:[1,0,1]
	v_pk_fma_f32 v[34:35], v[216:217], v[114:115], v[100:101] op_sel_hi:[1,0,1]
	v_pk_fma_f32 v[36:37], v[218:219], v[114:115], v[102:103] op_sel_hi:[1,0,1]
	v_lshlrev_b32_e32 v116, 16, v20
	v_and_b32_e32 v118, 0xffff0000, v20
	v_lshlrev_b32_e32 v120, 16, v21
	v_and_b32_e32 v122, 0xffff0000, v21
	v_pk_mul_f32 v[100:101], v[224:225], v[118:119] op_sel_hi:[1,0]
	v_pk_mul_f32 v[102:103], v[226:227], v[118:119] op_sel_hi:[1,0]
	v_pk_fma_f32 v[100:101], v[220:221], v[116:117], v[100:101] op_sel_hi:[1,0,1]
	v_pk_fma_f32 v[102:103], v[222:223], v[116:117], v[102:103] op_sel_hi:[1,0,1]
	v_pk_fma_f32 v[100:101], v[228:229], v[120:121], v[100:101] op_sel_hi:[1,0,1]
	v_pk_fma_f32 v[102:103], v[230:231], v[120:121], v[102:103] op_sel_hi:[1,0,1]
	v_pk_fma_f32 v[38:39], v[248:249], v[122:123], v[100:101] op_sel_hi:[1,0,1]
	v_pk_fma_f32 v[40:41], v[250:251], v[122:123], v[102:103] op_sel_hi:[1,0,1]
	v_cvt_pk_bf16_f32 v104, v34, v35
	v_cvt_pk_bf16_f32 v105, v36, v37
	v_cvt_pk_bf16_f32 v106, v38, v39
	v_cvt_pk_bf16_f32 v107, v40, v41
	ds_write_b128 v246, v[104:107] offset:33280
	s_waitcnt vmcnt(2)
	v_lshlrev_b32_e32 v108, 16, v22
	v_and_b32_e32 v110, 0xffff0000, v22
	v_lshlrev_b32_e32 v112, 16, v23
	v_and_b32_e32 v114, 0xffff0000, v23
	v_pk_mul_f32 v[100:101], v[208:209], v[110:111] op_sel_hi:[1,0]
	v_pk_mul_f32 v[102:103], v[210:211], v[110:111] op_sel_hi:[1,0]
	v_pk_fma_f32 v[100:101], v[204:205], v[108:109], v[100:101] op_sel_hi:[1,0,1]
	v_pk_fma_f32 v[102:103], v[206:207], v[108:109], v[102:103] op_sel_hi:[1,0,1]
	v_pk_fma_f32 v[100:101], v[212:213], v[112:113], v[100:101] op_sel_hi:[1,0,1]
	v_pk_fma_f32 v[102:103], v[214:215], v[112:113], v[102:103] op_sel_hi:[1,0,1]
	v_pk_fma_f32 v[34:35], v[216:217], v[114:115], v[100:101] op_sel_hi:[1,0,1]
	v_pk_fma_f32 v[36:37], v[218:219], v[114:115], v[102:103] op_sel_hi:[1,0,1]
	v_lshlrev_b32_e32 v116, 16, v24
	v_and_b32_e32 v118, 0xffff0000, v24
	v_lshlrev_b32_e32 v120, 16, v25
	v_and_b32_e32 v122, 0xffff0000, v25
	v_pk_mul_f32 v[100:101], v[224:225], v[118:119] op_sel_hi:[1,0]
	v_pk_mul_f32 v[102:103], v[226:227], v[118:119] op_sel_hi:[1,0]
	v_pk_fma_f32 v[100:101], v[220:221], v[116:117], v[100:101] op_sel_hi:[1,0,1]
	v_pk_fma_f32 v[102:103], v[222:223], v[116:117], v[102:103] op_sel_hi:[1,0,1]
	v_pk_fma_f32 v[100:101], v[228:229], v[120:121], v[100:101] op_sel_hi:[1,0,1]
	v_pk_fma_f32 v[102:103], v[230:231], v[120:121], v[102:103] op_sel_hi:[1,0,1]
	v_pk_fma_f32 v[38:39], v[248:249], v[122:123], v[100:101] op_sel_hi:[1,0,1]
	v_pk_fma_f32 v[40:41], v[250:251], v[122:123], v[102:103] op_sel_hi:[1,0,1]
	v_cvt_pk_bf16_f32 v104, v34, v35
	v_cvt_pk_bf16_f32 v105, v36, v37
	v_cvt_pk_bf16_f32 v106, v38, v39
	v_cvt_pk_bf16_f32 v107, v40, v41
	ds_write_b128 v246, v[104:107] offset:41600
	s_waitcnt vmcnt(1)
	v_lshlrev_b32_e32 v108, 16, v26
	v_and_b32_e32 v110, 0xffff0000, v26
	v_lshlrev_b32_e32 v112, 16, v27
	v_and_b32_e32 v114, 0xffff0000, v27
	v_pk_mul_f32 v[100:101], v[208:209], v[110:111] op_sel_hi:[1,0]
	v_pk_mul_f32 v[102:103], v[210:211], v[110:111] op_sel_hi:[1,0]
	v_pk_fma_f32 v[100:101], v[204:205], v[108:109], v[100:101] op_sel_hi:[1,0,1]
	v_pk_fma_f32 v[102:103], v[206:207], v[108:109], v[102:103] op_sel_hi:[1,0,1]
	v_pk_fma_f32 v[100:101], v[212:213], v[112:113], v[100:101] op_sel_hi:[1,0,1]
	v_pk_fma_f32 v[102:103], v[214:215], v[112:113], v[102:103] op_sel_hi:[1,0,1]
	v_pk_fma_f32 v[34:35], v[216:217], v[114:115], v[100:101] op_sel_hi:[1,0,1]
	v_pk_fma_f32 v[36:37], v[218:219], v[114:115], v[102:103] op_sel_hi:[1,0,1]
	v_lshlrev_b32_e32 v116, 16, v28
	v_and_b32_e32 v118, 0xffff0000, v28
	v_lshlrev_b32_e32 v120, 16, v29
	v_and_b32_e32 v122, 0xffff0000, v29
	v_pk_mul_f32 v[100:101], v[224:225], v[118:119] op_sel_hi:[1,0]
	v_pk_mul_f32 v[102:103], v[226:227], v[118:119] op_sel_hi:[1,0]
	v_pk_fma_f32 v[100:101], v[220:221], v[116:117], v[100:101] op_sel_hi:[1,0,1]
	v_pk_fma_f32 v[102:103], v[222:223], v[116:117], v[102:103] op_sel_hi:[1,0,1]
	v_pk_fma_f32 v[100:101], v[228:229], v[120:121], v[100:101] op_sel_hi:[1,0,1]
	v_pk_fma_f32 v[102:103], v[230:231], v[120:121], v[102:103] op_sel_hi:[1,0,1]
	v_pk_fma_f32 v[38:39], v[248:249], v[122:123], v[100:101] op_sel_hi:[1,0,1]
	v_pk_fma_f32 v[40:41], v[250:251], v[122:123], v[102:103] op_sel_hi:[1,0,1]
	v_cvt_pk_bf16_f32 v104, v34, v35
	v_cvt_pk_bf16_f32 v105, v36, v37
	v_cvt_pk_bf16_f32 v106, v38, v39
	v_cvt_pk_bf16_f32 v107, v40, v41
	ds_write_b128 v246, v[104:107] offset:49920
	s_waitcnt vmcnt(0)
	v_lshlrev_b32_e32 v108, 16, v30
	v_and_b32_e32 v110, 0xffff0000, v30
	v_lshlrev_b32_e32 v112, 16, v31
	v_and_b32_e32 v114, 0xffff0000, v31
	v_pk_mul_f32 v[100:101], v[208:209], v[110:111] op_sel_hi:[1,0]
	v_pk_mul_f32 v[102:103], v[210:211], v[110:111] op_sel_hi:[1,0]
	v_pk_fma_f32 v[100:101], v[204:205], v[108:109], v[100:101] op_sel_hi:[1,0,1]
	v_pk_fma_f32 v[102:103], v[206:207], v[108:109], v[102:103] op_sel_hi:[1,0,1]
	v_pk_fma_f32 v[100:101], v[212:213], v[112:113], v[100:101] op_sel_hi:[1,0,1]
	v_pk_fma_f32 v[102:103], v[214:215], v[112:113], v[102:103] op_sel_hi:[1,0,1]
	v_pk_fma_f32 v[34:35], v[216:217], v[114:115], v[100:101] op_sel_hi:[1,0,1]
	v_pk_fma_f32 v[36:37], v[218:219], v[114:115], v[102:103] op_sel_hi:[1,0,1]
	v_lshlrev_b32_e32 v116, 16, v32
	v_and_b32_e32 v118, 0xffff0000, v32
	v_lshlrev_b32_e32 v120, 16, v33
	v_and_b32_e32 v122, 0xffff0000, v33
	v_pk_mul_f32 v[100:101], v[224:225], v[118:119] op_sel_hi:[1,0]
	v_pk_mul_f32 v[102:103], v[226:227], v[118:119] op_sel_hi:[1,0]
	v_pk_fma_f32 v[100:101], v[220:221], v[116:117], v[100:101] op_sel_hi:[1,0,1]
	v_pk_fma_f32 v[102:103], v[222:223], v[116:117], v[102:103] op_sel_hi:[1,0,1]
	v_pk_fma_f32 v[100:101], v[228:229], v[120:121], v[100:101] op_sel_hi:[1,0,1]
	v_pk_fma_f32 v[102:103], v[230:231], v[120:121], v[102:103] op_sel_hi:[1,0,1]
	v_pk_fma_f32 v[38:39], v[248:249], v[122:123], v[100:101] op_sel_hi:[1,0,1]
	v_pk_fma_f32 v[40:41], v[250:251], v[122:123], v[102:103] op_sel_hi:[1,0,1]
	v_cvt_pk_bf16_f32 v104, v34, v35
	v_cvt_pk_bf16_f32 v105, v36, v37
	v_cvt_pk_bf16_f32 v106, v38, v39
	v_cvt_pk_bf16_f32 v107, v40, v41
	ds_write_b128 v246, v[104:107] offset:58240
	s_and_saveexec_b64 s[56:57], s[4:5]
	s_cbranch_execz .LBB0_677
	s_lshl_b32 s80, s63, 2
	v_mov_b32_e32 v36, s80
	global_load_dword v37, v36, s[2:3] offset:16
	v_mov_b32_e32 v35, s55
	v_or_b32_e32 v34, s54, v46
	v_lshlrev_b64 v[34:35], 7, v[34:35]
	v_lshl_add_u64 v[34:35], s[48:49], 0, v[34:35]
	v_lshl_add_u64 v[34:35], v[34:35], 0, s[80:81]
	global_load_dword v38, v[34:35], off offset:16
	global_load_dword v39, v[34:35], off offset:48
	global_load_dword v40, v[34:35], off offset:80
	global_load_dword v41, v[34:35], off offset:112
	s_nop 0
	global_load_dword v36, v36, s[2:3]
	s_nop 0
	global_load_dword v57, v[34:35], off offset:96
	global_load_dword v59, v[34:35], off offset:64
	global_load_dword v100, v[34:35], off offset:32
	s_nop 0
	global_load_dword v34, v[34:35], off
	s_waitcnt vmcnt(8)
	v_add_f32_e32 v35, v37, v38
	s_waitcnt vmcnt(7)
	v_add_f32_e32 v35, v35, v39
	s_waitcnt vmcnt(6)
	v_add_f32_e32 v35, v35, v40
	s_waitcnt vmcnt(5)
	v_add_f32_e32 v35, v35, v41
	v_mul_f32_e64 v37, |v35|, s72
	v_exp_f32_e32 v37, v37
	v_add_u32_e32 v38, -1, v234
	v_cmp_lt_i32_e64 s[44:45], v38, v242
	v_max_f32_e64 v35, -v35, 0
	v_add_f32_e32 v37, 1.0, v37
	v_cndmask_b32_e64 v38, v38, v234, s[44:45]
	v_cmp_gt_f32_e64 s[44:45], s71, v37
	v_lshlrev_b32_e32 v38, 2, v38
	s_waitcnt vmcnt(0)
	v_add_f32_e32 v34, v36, v34
	v_cndmask_b32_e64 v39, 0, 32, s[44:45]
	v_ldexp_f32 v37, v37, v39
	v_log_f32_e32 v37, v37
	v_cndmask_b32_e64 v39, 0, v243, s[44:45]
	v_add_f32_e32 v34, v34, v100
	v_add_f32_e32 v34, v34, v59
	v_mul_f32_e32 v40, 0x3f317217, v37
	v_fma_f32 v40, v37, s73, -v40
	v_fmac_f32_e32 v40, 0x3377d1cf, v37
	v_fmac_f32_e32 v40, 0x3f317217, v37
	v_cmp_lt_f32_e64 s[44:45], |v37|, s74
	v_add_f32_e32 v36, v34, v57
	s_nop 0
	v_cndmask_b32_e64 v37, v37, v40, s[44:45]
	v_sub_f32_e32 v37, v37, v39
	v_add_f32_e32 v35, v35, v37
	v_xor_b32_e32 v37, 0x80000000, v35
	ds_bpermute_b32 v37, v38, v37
	v_add_u32_e32 v38, -2, v234
	v_cmp_lt_i32_e64 s[44:45], v38, v242
	s_waitcnt lgkmcnt(0)
	v_sub_f32_e32 v37, v37, v35
	v_cndmask_b32_e64 v38, v38, v234, s[44:45]
	v_lshlrev_b32_e32 v38, 2, v38
	v_cndmask_b32_e64 v35, v37, -v35, s[6:7]
	ds_bpermute_b32 v37, v38, v35
	v_add_u32_e32 v38, -4, v234
	v_cmp_lt_i32_e64 s[44:45], v38, v242
	s_waitcnt lgkmcnt(0)
	v_add_f32_e32 v37, v35, v37
	v_cndmask_b32_e64 v38, v38, v234, s[44:45]
	v_lshlrev_b32_e32 v38, 2, v38
	v_cndmask_b32_e64 v35, v37, v35, s[14:15]
	ds_bpermute_b32 v37, v38, v35
	v_add_u32_e32 v38, -8, v234
	v_cmp_lt_i32_e64 s[44:45], v38, v242
	s_waitcnt lgkmcnt(0)
	v_add_f32_e32 v37, v35, v37
	v_cndmask_b32_e64 v38, v38, v234, s[44:45]
	v_lshlrev_b32_e32 v38, 2, v38
	v_cndmask_b32_e64 v35, v37, v35, s[16:17]
	ds_bpermute_b32 v37, v38, v35
	v_add_u32_e32 v38, -16, v234
	v_cmp_lt_i32_e64 s[44:45], v38, v242
	s_waitcnt lgkmcnt(0)
	v_add_f32_e32 v37, v35, v37
	v_cndmask_b32_e64 v38, v38, v234, s[44:45]
	v_lshlrev_b32_e32 v38, 2, v38
	v_cndmask_b32_e64 v35, v37, v35, s[18:19]
	ds_bpermute_b32 v37, v38, v35
	v_subrev_u32_e32 v38, 32, v234
	v_cmp_lt_i32_e64 s[44:45], v38, v242
	s_waitcnt lgkmcnt(0)
	v_add_f32_e32 v37, v35, v37
	v_cndmask_b32_e64 v38, v38, v234, s[44:45]
	v_lshlrev_b32_e32 v38, 2, v38
	v_cndmask_b32_e64 v35, v37, v35, s[10:11]
	ds_bpermute_b32 v37, v38, v35
	s_waitcnt lgkmcnt(0)
	v_add_f32_e32 v34, v35, v37
	v_cndmask_b32_e64 v35, v34, v35, s[20:21]
	v_lshl_or_b32 v34, v234, 2, v244
	ds_bpermute_b32 v34, v34, v35
	ds_write_b32 v1, v35
	ds_write_b32 v47, v36
	v_mul_f32_e32 v37, 0x3fb8aa3b, v35
	v_exp_f32_e32 v37, v37
	s_waitcnt lgkmcnt(2)
	v_sub_f32_e32 v35, v34, v35
	v_add_f32_e32 v35, v36, v35
	v_mul_f32_e32 v35, 0x3fb8aa3b, v35
	v_exp_f32_e32 v35, v35
	v_lshlrev_b32_e32 v36, 2, v46
	global_store_dword v36, v37, s[50:51]
	v_lshl_add_u64 v[36:37], v[42:43], 2, s[50:51]
	global_store_dword v[36:37], v35, off offset:256
	s_and_b64 exec, exec, s[6:7]
	s_cbranch_execz .LBB0_677
	v_mul_f32_e32 v34, 0x3fb8aa3b, v34
	v_exp_f32_e32 v34, v34
	global_store_dword v0, v34, s[50:51] offset:768

.Lmli_noq:
	s_or_b64 exec, exec, s[64:65]
	s_mov_b32 s44, s70
	s_waitcnt lgkmcnt(0)
	s_barrier
	s_add_i32 s44, s44, s33
	s_cmpk_gt_i32 s44, 0x7ff
	s_cselect_b32 s65, 0, 1
	s_cbranch_scc1 .LBB0_679
	s_ashr_i32 s56, s44, 9
	s_ashr_i32 s57, s56, 31
	s_lshl_b32 s45, s44, 4
	s_and_b32 s80, s45, 0x1fc0
	s_lshl_b64 s[56:57], s[56:57], 25
	v_lshl_add_u64 v[2:3], s[80:81], 0, v[236:237]
	s_add_u32 s56, s46, s56
	v_lshlrev_b64 v[2:3], 12, v[2:3]
	s_addc_u32 s57, s47, s57
	s_lshl_b32 s44, s44, 10
	v_lshl_add_u64 v[2:3], s[56:57], 0, v[2:3]
	s_and_b32 s80, s44, 0xc00
	v_lshl_add_u64 v[2:3], v[2:3], 0, s[80:81]
	v_mov_b32_e32 v57, v0
	v_lshl_add_u64 v[232:233], v[2:3], 0, v[238:239]
	global_load_dwordx4 v[2:5], v[232:233], off
	v_lshl_add_u64 v[232:233], v[232:233], 0, v[252:253]
	global_load_dwordx4 v[6:9], v[232:233], off
	v_lshl_add_u64 v[232:233], v[232:233], 0, v[252:253]
	global_load_dwordx4 v[10:13], v[232:233], off
	v_lshl_add_u64 v[232:233], v[232:233], 0, v[252:253]
	global_load_dwordx4 v[14:17], v[232:233], off
	v_lshl_add_u64 v[232:233], v[232:233], 0, v[252:253]
	global_load_dwordx4 v[18:21], v[232:233], off
	v_lshl_add_u64 v[232:233], v[232:233], 0, v[252:253]
	global_load_dwordx4 v[22:25], v[232:233], off
	v_lshl_add_u64 v[232:233], v[232:233], 0, v[252:253]
	global_load_dwordx4 v[26:29], v[232:233], off
	v_lshl_add_u64 v[232:233], v[232:233], 0, v[252:253]
	global_load_dwordx4 v[30:33], v[232:233], off
